# half-k-step entry offset (s_sleep 26) for one of the two co-resident blocks in the four GEMM phases
# baseline (speedup 1.0000x reference)
.LBB0_141:
	s_or_b64 exec, exec, s[0:1]
	s_mov_b64 s[0:1], s[56:57]
	s_waitcnt lgkmcnt(0)
	s_barrier
	s_lshr_b32 s98, s12, 3
	s_lshr_b32 s99, s12, 8
	s_xor_b32 s98, s98, s99
	s_bitcmp1_b32 s98, 0
	s_cbranch_scc0 .Lstg_gemm1_skip
	s_mov_b32 s98, 1
.Lstg_gemm1_loop:
	s_sleep 26
	s_sub_u32 s98, s98, 1
	s_cmp_lg_u32 s98, 0
	s_cbranch_scc1 .Lstg_gemm1_loop
.Lstg_gemm1_skip:
	s_add_u32 s2, s0, 0x4000000
	s_addc_u32 s3, s1, 0
	s_add_u32 s22, s0, 0x18000000
	s_addc_u32 s23, s1, 0
	s_add_u32 s26, s0, 0x1c000000
	s_mov_b64 s[18:19], s[54:55]
	s_addc_u32 s27, s1, 0
	s_add_u32 s30, s18, 0x4000000
	s_addc_u32 s31, s19, 0
	s_add_u32 s46, s0, 0x3e00000
	s_addc_u32 s47, s1, 0
	s_lshr_b32 s94, s58, 3
	v_cvt_f32_u32_e32 v0, s94
	v_writelane_b32 v255, s2, 5
	s_mov_b32 s33, 0
	s_mov_b32 s88, 0
	v_rcp_iflag_f32_e32 v1, v0
	v_writelane_b32 v255, s3, 6
	s_sub_i32 s3, 0, s94
	s_add_i32 s2, s94, 0x3ff
	v_mul_f32_e32 v1, 0x4f7ffffe, v1
	v_cvt_u32_f32_e32 v1, v1
	v_mov_b32_e32 v0, v196
	s_mov_b32 s14, 0
	v_readfirstlane_b32 s4, v1
	s_mul_i32 s3, s3, s4
	s_mul_hi_u32 s3, s4, s3
	s_add_i32 s4, s4, s3
	s_mul_hi_u32 s3, s2, s4
	s_mul_i32 s4, s3, s94
	s_sub_i32 s2, s2, s4
	s_add_i32 s4, s3, 1
	s_sub_i32 s5, s2, s94
	s_cmp_ge_u32 s2, s94
	s_cselect_b32 s3, s4, s3
	s_cselect_b32 s2, s5, s2
	s_add_i32 s4, s3, 1
	s_cmp_ge_u32 s2, s94
	s_cselect_b32 s86, s4, s3
	s_cmpk_lt_i32 s12, 0x100
	s_cselect_b64 s[6:7], -1, 0
	s_lshr_b32 s95, s12, 3
	s_lshl_b32 s2, s12, 5
	s_and_b32 s96, s2, 0xe0
	s_mov_b32 s10, s95
	s_cmp_ge_u32 s33, s86
	s_cselect_b64 s[2:3], -1, 0
	s_and_b64 vcc, exec, s[2:3]
	s_cbranch_vccnz .LBB0_143
	s_branch .LBB0_144

.LBB0_879:
	s_or_b64 exec, exec, s[0:1]
	s_add_u32 s28, s56, 0x1c000000
	s_addc_u32 s29, s57, 0
	s_add_u32 s0, s56, 0x900000
	s_addc_u32 s1, s57, 0
	s_cmpk_lt_u32 s12, 0x800
	s_mov_b64 s[2:3], s[28:29]
	v_mov_b32_e32 v0, v196
	s_cselect_b64 s[24:25], -1, 0
	s_cmpk_gt_u32 s12, 0x7ff
	s_waitcnt lgkmcnt(0)
	s_barrier
	s_cbranch_scc1 .LBB0_892
	s_lshr_b32 s98, s12, 3
	s_lshr_b32 s99, s12, 8
	s_xor_b32 s98, s98, s99
	s_bitcmp1_b32 s98, 0
	s_cbranch_scc0 .Lstg_gres1_skip
	s_mov_b32 s98, 1

.LBB0_1001:
	s_or_b64 exec, exec, s[0:1]
	s_mov_b64 s[16:17], s[56:57]
	v_mov_b32_e32 v0, v196
	s_cmpk_gt_u32 s12, 0x1fff
	s_waitcnt lgkmcnt(0)
	s_barrier
	s_cbranch_scc1 .LBB0_1030
	s_lshr_b32 s98, s12, 3
	s_lshr_b32 s99, s12, 8
	s_xor_b32 s98, s98, s99
	s_bitcmp1_b32 s98, 0
	s_cbranch_scc0 .Lstg_kvq_skip
	s_mov_b32 s98, 1

.Lstg_kvq_skip:
	s_add_u32 s36, s16, 0x4000000
	s_addc_u32 s37, s17, 0
	s_add_u32 s38, s16, 0xb00000
	s_addc_u32 s39, s17, 0
	s_add_u32 s40, s16, 0x10000000
	s_addc_u32 s41, s17, 0
	s_add_u32 s42, s16, 0x18000000
	s_addc_u32 s43, s17, 0
	s_add_u32 s44, s16, 0x1540000
	s_addc_u32 s45, s17, 0
	s_lshr_b32 s0, s12, 11
	s_lshl_b32 s1, s0, 3
	s_bfe_u32 s2, s12, 0x30003
	s_or_b32 s1, s1, s2
	s_or_b32 s70, s1, s96
	s_lshr_b32 s1, s12, 6
	s_lshl_b32 s0, s0, 5
	s_and_b32 s1, s1, 0x78
	v_mov_b32_e32 v4, v196
	s_sub_i32 s0, s1, s0
	s_bfe_u32 s1, s12, 0x30006
	s_lshl_b32 s10, s70, 7
	s_or_b32 s48, s0, s1
	v_ashrrev_i32_e32 v5, 3, v4
	v_add_u32_e32 v2, s10, v5
	s_lshl_b32 s11, s48, 7
	v_ashrrev_i32_e32 v3, 31, v2
	v_lshlrev_b32_e32 v4, 4, v4
	v_lshlrev_b64 v[2:3], 11, v[2:3]
	v_and_b32_e32 v130, 0x70, v4
	v_add_u32_e32 v4, s11, v5
	v_lshl_add_u64 v[2:3], s[36:37], 0, v[2:3]
	v_mov_b32_e32 v131, 0
	v_ashrrev_i32_e32 v5, 31, v4
	v_lshl_add_u64 v[2:3], v[2:3], 0, v[130:131]
	v_lshlrev_b64 v[4:5], 11, v[4:5]
	s_mov_b32 s15, 0x10000
	v_lshl_add_u64 v[4:5], s[38:39], 0, v[4:5]
	v_add_co_u32_e32 v6, vcc, s15, v2
	v_lshl_add_u64 v[4:5], v[4:5], 0, v[130:131]
	s_nop 0
	v_addc_co_u32_e32 v7, vcc, 0, v3, vcc
	v_add_co_u32_e32 v8, vcc, s15, v4
	s_mov_b32 s33, 0x20000
	s_nop 0
	v_addc_co_u32_e32 v9, vcc, 0, v5, vcc
	v_add_co_u32_e32 v10, vcc, s33, v2
	s_mov_b32 s0, 0x30000
	s_nop 0
	v_addc_co_u32_e32 v11, vcc, 0, v3, vcc
	v_add_co_u32_e32 v12, vcc, s33, v4
	v_and_b32_e32 v129, 63, v0
	s_nop 0
	v_addc_co_u32_e32 v13, vcc, 0, v5, vcc
	v_add_co_u32_e32 v14, vcc, s0, v2
	v_ashrrev_i32_e32 v1, 6, v0
	s_nop 0
	v_addc_co_u32_e32 v15, vcc, 0, v3, vcc
	v_add_co_u32_e32 v16, vcc, s0, v4
	s_movk_i32 s0, 0x2400
	s_nop 0
	v_addc_co_u32_e32 v17, vcc, 0, v5, vcc
	global_load_dwordx4 v[64:67], v[2:3], off
	global_load_dwordx4 v[68:71], v[2:3], off offset:128
	global_load_dwordx4 v[72:75], v[4:5], off
	global_load_dwordx4 v[76:79], v[4:5], off offset:128
	global_load_dwordx4 v[80:83], v[6:7], off
	global_load_dwordx4 v[84:87], v[6:7], off offset:128
	global_load_dwordx4 v[88:91], v[8:9], off
	global_load_dwordx4 v[92:95], v[8:9], off offset:128
	global_load_dwordx4 v[96:99], v[10:11], off
	global_load_dwordx4 v[100:103], v[10:11], off offset:128
	global_load_dwordx4 v[104:107], v[12:13], off
	global_load_dwordx4 v[108:111], v[12:13], off offset:128
	global_load_dwordx4 v[112:115], v[14:15], off
	global_load_dwordx4 v[116:119], v[14:15], off offset:128
	global_load_dwordx4 v[120:123], v[16:17], off
	global_load_dwordx4 v[124:127], v[16:17], off offset:128
	v_bfe_u32 v3, v0, 3, 3
	v_and_b32_e32 v4, 4, v3
	v_mul_u32_u24_e32 v199, 0x90, v4
	v_or_b32_e32 v4, 3, v3
	s_waitcnt vmcnt(0)
	v_mul_u32_u24_e32 v200, 0x90, v4
	v_or_b32_e32 v4, 11, v3
	v_mul_u32_u24_e32 v201, 0x90, v4
	v_or_b32_e32 v4, 19, v3
	v_and_b32_e32 v133, 1, v1
	v_mul_lo_u32 v1, v1, s0
	v_lshlrev_b32_e32 v5, 1, v129
	v_mul_u32_u24_e32 v202, 0x90, v4
	v_or_b32_e32 v4, 27, v3
	v_add_u32_e32 v1, 16, v1
	v_mul_u32_u24_e32 v203, 0x90, v4
	v_or_b32_e32 v4, 64, v5
	v_add_u32_e32 v204, v1, v4
	v_or_b32_e32 v4, 35, v3
	v_mul_u32_u24_e32 v205, 0x90, v4
	v_or_b32_e32 v4, 43, v3
	v_mul_u32_u24_e32 v206, 0x90, v4
	v_or_b32_e32 v4, 51, v3
	v_mul_u32_u24_e32 v207, 0x90, v4
	v_or_b32_e32 v4, 59, v3
	v_lshrrev_b32_e32 v20, 2, v0
	v_and_b32_e32 v128, 31, v0
	v_ashrrev_i32_e32 v2, 1, v0
	v_and_b32_e32 v6, 62, v5
	s_movk_i32 s0, 0x90
	v_mul_u32_u24_e32 v208, 0x90, v4
	v_and_b32_e32 v4, 7, v0
	v_or_b32_e32 v5, 8, v3
	v_or_b32_e32 v7, 16, v3
	v_or_b32_e32 v9, 24, v3
	v_or_b32_e32 v11, 32, v3
	v_or_b32_e32 v13, 40, v3
	v_or_b32_e32 v15, 48, v3
	v_or_b32_e32 v17, 56, v3
	v_and_b32_e32 v21, 8, v20
	v_or_b32_e32 v20, 32, v129
	v_and_b32_e32 v0, 39, v0
	v_and_b32_e32 v145, 0xffffffc0, v2
	v_lshlrev_b32_e32 v2, 6, v133
	v_add_u32_e32 v198, v1, v6
	v_lshl_add_u32 v209, v4, 4, v1
	v_lshlrev_b32_e32 v132, 3, v4
	v_lshlrev_b32_e32 v4, 10, v3
	v_lshlrev_b32_e32 v6, 10, v5
	v_lshlrev_b32_e32 v8, 10, v7
	v_lshlrev_b32_e32 v10, 10, v9
	v_lshlrev_b32_e32 v12, 10, v11
	v_lshlrev_b32_e32 v14, 10, v13
	v_lshlrev_b32_e32 v16, 10, v15
	v_lshlrev_b32_e32 v18, 10, v17
	v_mad_u32_u24 v19, v128, s0, v1
	v_mad_u32_u24 v23, v20, s0, v1
	v_lshlrev_b32_e32 v20, 13, v3
	v_lshlrev_b32_e32 v22, 13, v5
	v_lshlrev_b32_e32 v24, 13, v7
	v_lshlrev_b32_e32 v26, 13, v9
	v_lshlrev_b32_e32 v28, 13, v11
	v_lshlrev_b32_e32 v30, 13, v13
	v_lshlrev_b32_e32 v32, 13, v15
	v_lshlrev_b32_e32 v34, 13, v17
	v_lshl_add_u32 v212, v0, 3, v1
	s_add_u32 s50, s16, 0x2800000
	v_lshlrev_b32_e32 v0, 6, v3
	v_lshlrev_b32_e32 v36, 6, v5
	v_lshlrev_b32_e32 v38, 6, v7
	v_lshlrev_b32_e32 v40, 6, v9
	v_lshlrev_b32_e32 v42, 6, v11
	v_lshlrev_b32_e32 v44, 6, v13
	v_lshlrev_b32_e32 v46, 6, v15
	v_lshlrev_b32_e32 v48, 6, v17
	s_movk_i32 s14, 0x70
	s_mov_b32 s49, 0
	v_mul_u32_u24_e32 v210, 0x90, v3
	v_lshl_add_u32 v211, v129, 3, v1
	v_cmp_gt_u32_e64 s[2:3], 8, v128
	v_cmp_gt_u32_e64 s[4:5], 16, v128
	s_addc_u32 s51, s17, 0
	v_cmp_gt_u32_e64 s[6:7], 32, v129
	s_mov_b32 s35, 0x1ffffc0
	s_mov_b64 s[52:53], 0x100
	v_lshlrev_b32_e32 v134, 1, v2
	v_lshlrev_b32_e32 v136, 1, v4
	v_lshlrev_b32_e32 v138, 1, v6
	v_lshlrev_b32_e32 v140, 1, v8
	v_lshlrev_b32_e32 v142, 1, v10
	v_lshlrev_b32_e32 v148, 1, v12
	v_lshlrev_b32_e32 v150, 1, v14
	v_lshlrev_b32_e32 v152, 1, v16
	v_lshlrev_b32_e32 v154, 1, v18
	v_add_u32_e32 v213, v19, v21
	v_add_u32_e32 v214, v23, v21
	v_lshlrev_b32_e32 v156, 1, v20
	v_lshlrev_b32_e32 v158, 1, v22
	v_lshlrev_b32_e32 v160, 1, v24
	v_lshlrev_b32_e32 v162, 1, v26
	v_lshlrev_b32_e32 v164, 1, v28
	v_lshlrev_b32_e32 v166, 1, v30
	v_lshlrev_b32_e32 v168, 1, v32
	v_lshlrev_b32_e32 v170, 1, v34
	s_mov_b32 s62, 0x3c800000
	s_mov_b32 s64, 0x358637bd
	s_mov_b32 s46, 0x800000
	s_brev_b32 s47, 48
	v_lshlrev_b32_e32 v172, 1, v0
	v_lshlrev_b32_e32 v174, 1, v36
	v_lshlrev_b32_e32 v176, 1, v38
	v_lshlrev_b32_e32 v178, 1, v40
	v_lshlrev_b32_e32 v180, 1, v42
	v_lshlrev_b32_e32 v182, 1, v44
	v_lshlrev_b32_e32 v184, 1, v46
	v_lshlrev_b32_e32 v186, 1, v48
	v_mov_b32_e32 v215, 0x3e38aa3b
	v_mbcnt_hi_u32_b32 v216, -1, v253
	s_mov_b32 s63, s95
	s_mov_b32 s72, 0
	s_mov_b32 s65, 0
	s_branch .LBB0_1006

.LBB0_1501:
	s_or_b64 exec, exec, s[0:1]
	s_add_u32 s0, s56, 0x1300000
	s_addc_u32 s1, s57, 0
	v_mov_b32_e32 v0, v196
	s_andn2_b64 vcc, exec, s[24:25]
	s_waitcnt lgkmcnt(0)
	s_barrier
	s_cbranch_vccnz .LBB0_1514
	s_lshr_b32 s98, s12, 3
	s_lshr_b32 s99, s12, 8
	s_xor_b32 s98, s98, s99
	s_bitcmp1_b32 s98, 0
	s_cbranch_scc0 .Lstg_gres2_skip
	s_mov_b32 s98, 1
